# k49 + accumulator clears at GEMM unit start merged into v_mov_b64 (no phase-5 cache touch)
# baseline (speedup 1.0000x reference)
.LBB0_1032:
	s_ashr_i32 s25, s24, 31
	s_lshl_b64 s[26:27], s[24:25], 20
	s_add_u32 s26, s8, s26
	s_addc_u32 s27, s9, s27
	s_and_b64 s[28:29], s[0:1], exec
	s_cselect_b32 s25, s27, s35
	s_cselect_b32 s52, s26, s34
	s_ashr_i32 s23, s22, 31
	s_lshl_b64 s[28:29], s[22:23], 20
	v_readlane_b32 s38, v249, 39
	v_readlane_b32 s39, v249, 40
	s_add_u32 s28, s38, s28
	s_addc_u32 s29, s39, s29
	s_and_b64 s[38:39], s[0:1], exec
	s_cselect_b32 s23, s29, s37
	s_cselect_b32 s53, s28, s36
	s_add_u32 s34, s34, 0x80080
	s_addc_u32 s35, s35, 0
	s_add_u32 s54, s36, 0x100
	v_mov_b64_e32 v[0:1], 0
	s_addc_u32 s55, s37, 0
	s_mov_b32 s56, -2
	v_mov_b64_e32 v[2:3], 0
	v_mov_b64_e32 v[4:5], 0
	v_mov_b64_e32 v[6:7], 0
	v_mov_b64_e32 v[8:9], 0
	v_mov_b64_e32 v[10:11], 0
	v_mov_b64_e32 v[20:21], 0
	v_mov_b64_e32 v[22:23], 0
	v_mov_b64_e32 v[24:25], 0
	v_mov_b64_e32 v[26:27], 0
	v_mov_b64_e32 v[36:37], 0
	v_mov_b64_e32 v[38:39], 0
	v_mov_b64_e32 v[40:41], 0
	v_mov_b64_e32 v[42:43], 0
	v_mov_b64_e32 v[52:53], 0
	v_mov_b64_e32 v[54:55], 0
	v_mov_b64_e32 v[12:13], 0
	v_mov_b64_e32 v[14:15], 0
	v_mov_b64_e32 v[16:17], 0
	v_mov_b64_e32 v[18:19], 0
	v_mov_b64_e32 v[28:29], 0
	v_mov_b64_e32 v[30:31], 0
	v_mov_b64_e32 v[32:33], 0
	v_mov_b64_e32 v[34:35], 0
	v_mov_b64_e32 v[44:45], 0
	v_mov_b64_e32 v[46:47], 0
	v_mov_b64_e32 v[48:49], 0
	v_mov_b64_e32 v[50:51], 0
	v_mov_b64_e32 v[56:57], 0
	v_mov_b64_e32 v[58:59], 0
	v_mov_b64_e32 v[60:61], 0
	v_mov_b64_e32 v[62:63], 0
	v_mov_b64_e32 v[64:65], 0
	v_mov_b64_e32 v[66:67], 0
	v_mov_b64_e32 v[68:69], 0
	v_mov_b64_e32 v[70:71], 0
	v_mov_b64_e32 v[72:73], 0
	v_mov_b64_e32 v[74:75], 0
	v_mov_b64_e32 v[84:85], 0
	v_mov_b64_e32 v[86:87], 0
	v_mov_b64_e32 v[88:89], 0
	v_mov_b64_e32 v[90:91], 0
	v_mov_b64_e32 v[100:101], 0
	v_mov_b64_e32 v[102:103], 0
	v_mov_b64_e32 v[104:105], 0
	v_mov_b64_e32 v[106:107], 0
	v_mov_b64_e32 v[116:117], 0
	v_mov_b64_e32 v[118:119], 0
	v_mov_b64_e32 v[76:77], 0
	v_mov_b64_e32 v[78:79], 0
	v_mov_b64_e32 v[80:81], 0
	v_mov_b64_e32 v[82:83], 0
	v_mov_b64_e32 v[92:93], 0
	v_mov_b64_e32 v[94:95], 0
	v_mov_b64_e32 v[96:97], 0
	v_mov_b64_e32 v[98:99], 0
	v_mov_b64_e32 v[108:109], 0
	v_mov_b64_e32 v[110:111], 0
	v_mov_b64_e32 v[112:113], 0
	v_mov_b64_e32 v[114:115], 0
	v_mov_b64_e32 v[120:121], 0
	v_mov_b64_e32 v[122:123], 0
	v_mov_b64_e32 v[124:125], 0
	v_mov_b64_e32 v[126:127], 0
